# plus: out-proj and down-proj GEMM tile epilogues issue all their residual loads up front instead of 16 load-wait-store steps
# speedup vs baseline: 1.0256x; 1.0007x over previous
; DI u32x4 pack8f(const f32x4& a, const f32x4& b) { u32x4 w; w.x = pk2(a[0], a[1]); w.y = pk2(a[2], a[3]); w.z = pk2(b[0], b[1]); w.w = pk2(b[2], b[3]); return w; }
;     __device__ __forceinline__ void operator()(const f32x4 (&acc)[2][2][4][2], const Unit& u, int wr, int wc, int fr, int fq) const {
; #pragma unroll
;         for (int ai = 0; ai < 2; ++ai)
; #pragma unroll
;             for (int m = 0; m < 4; ++m) {
;                 const int row = u.pm * BM + ai * HALF + wr * 64 + m * 16 + fr;
;                 const float* xrow = xp + (size_t)row * DM;
;                 float ss = 0.f;
; #pragma unroll
;                 for (int bj = 0; bj < 2; ++bj) {
;                     const int col = u.pn * BM + bj * HALF + wc * 32 + 8 * fq;
;                     const f32x4 v0 = acc[ai][bj][m][0] + __builtin_nontemporal_load((const f32x4*)(xrow + col)), v1 = acc[ai][bj][m][1] + __builtin_nontemporal_load((const f32x4*)(xrow + col + 4));
;                     ss += (v0[0] * v0[0] + v0[1] * v0[1]) + (v0[2] * v0[2] + v0[3] * v0[3]) + (v1[0] * v1[0] + v1[1] * v1[1]) + (v1[2] * v1[2] + v1[3] * v1[3]);
;                     *(u32x4*)(X1B + (size_t)row * DM + col) = pack8f(v0, v1);
;                 }
;                 ss += __shfl_xor(ss, 16); ss += __shfl_xor(ss, 32);
.LBB0_530:
	v_lshl_add_u32 v170, s26, 8, v154
	v_lshl_or_b32 v171, s8, 8, v157
	v_lshlrev_b32_e32 v240, 13, v170
	v_lshl_add_u32 v240, v171, 2, v240
	v_add_u32_e32 v241, 0x20000, v240
	v_add_u32_e32 v242, 0x40000, v240
	v_add_u32_e32 v243, 0x60000, v240
	v_add_u32_e32 v244, 0x100000, v240
	v_add_u32_e32 v245, 0x120000, v240
	v_add_u32_e32 v246, 0x140000, v240
	v_add_u32_e32 v247, 0x160000, v240
	v_xor_b32_e32 v172, 16, v161
	v_xor_b32_e32 v173, 32, v161
	v_lshlrev_b32_e32 v172, 2, v172
	v_lshlrev_b32_e32 v173, 2, v173
	global_load_dwordx4 v[176:179], v240, s[44:45] nt
	global_load_dwordx4 v[180:183], v240, s[44:45] offset:16 nt
	global_load_dwordx4 v[184:187], v240, s[44:45] offset:512 nt
	global_load_dwordx4 v[188:191], v240, s[44:45] offset:528 nt
	global_load_dwordx4 v[192:195], v241, s[44:45] nt
	global_load_dwordx4 v[196:199], v241, s[44:45] offset:16 nt
	global_load_dwordx4 v[200:203], v241, s[44:45] offset:512 nt
	global_load_dwordx4 v[204:207], v241, s[44:45] offset:528 nt
	global_load_dwordx4 v[208:211], v242, s[44:45] nt
	global_load_dwordx4 v[212:215], v242, s[44:45] offset:16 nt
	global_load_dwordx4 v[216:219], v242, s[44:45] offset:512 nt
	global_load_dwordx4 v[220:223], v242, s[44:45] offset:528 nt
	global_load_dwordx4 v[224:227], v243, s[44:45] nt
	global_load_dwordx4 v[228:231], v243, s[44:45] offset:16 nt
	global_load_dwordx4 v[232:235], v243, s[44:45] offset:512 nt
	global_load_dwordx4 v[236:239], v243, s[44:45] offset:528 nt
	s_waitcnt vmcnt(12)
	v_lshrrev_b32_e32 v144, 1, v240
	v_pk_add_f32 v[176:177], v[124:125], v[176:177]
	v_pk_add_f32 v[178:179], v[126:127], v[178:179]
	v_pk_add_f32 v[180:181], v[120:121], v[180:181]
	v_pk_add_f32 v[182:183], v[122:123], v[182:183]
	v_cvt_pk_bf16_f32 v248, v176, v177
	v_cvt_pk_bf16_f32 v249, v178, v179
	v_cvt_pk_bf16_f32 v250, v180, v181
	v_cvt_pk_bf16_f32 v251, v182, v183
	global_store_dwordx4 v144, v[248:251], s[66:67]
	v_mul_f32_e32 v177, v177, v177
	v_mul_f32_e32 v179, v179, v179
	v_mul_f32_e32 v181, v181, v181
	v_mul_f32_e32 v183, v183, v183
	v_fmac_f32_e32 v177, v176, v176
	v_fmac_f32_e32 v179, v178, v178
	v_fmac_f32_e32 v181, v180, v180
	v_fmac_f32_e32 v183, v182, v182
	v_add_f32_e32 v145, v177, v179
	v_add_f32_e32 v145, v145, v181
	v_add_f32_e32 v162, v183, v145
	v_pk_add_f32 v[184:185], v[116:117], v[184:185]
	v_pk_add_f32 v[186:187], v[118:119], v[186:187]
	v_pk_add_f32 v[188:189], v[112:113], v[188:189]
	v_pk_add_f32 v[190:191], v[114:115], v[190:191]
	v_cvt_pk_bf16_f32 v248, v184, v185
	v_cvt_pk_bf16_f32 v249, v186, v187
	v_cvt_pk_bf16_f32 v250, v188, v189
	v_cvt_pk_bf16_f32 v251, v190, v191
	global_store_dwordx4 v144, v[248:251], s[66:67] offset:256
	v_mul_f32_e32 v185, v185, v185
	v_mul_f32_e32 v187, v187, v187
	v_mul_f32_e32 v189, v189, v189
	v_mul_f32_e32 v191, v191, v191
	v_fmac_f32_e32 v185, v184, v184
	v_fmac_f32_e32 v187, v186, v186
	v_fmac_f32_e32 v189, v188, v188
	v_fmac_f32_e32 v191, v190, v190
	v_add_f32_e32 v145, v185, v187
	v_add_f32_e32 v145, v145, v189
	v_add_f32_e32 v145, v191, v145
	v_add_f32_e32 v162, v162, v145
	global_load_dwordx4 v[176:179], v244, s[44:45] nt
	global_load_dwordx4 v[180:183], v244, s[44:45] offset:16 nt
	global_load_dwordx4 v[184:187], v244, s[44:45] offset:512 nt
	global_load_dwordx4 v[188:191], v244, s[44:45] offset:528 nt
	s_waitcnt vmcnt(14)
	v_lshrrev_b32_e32 v144, 1, v241
	v_pk_add_f32 v[192:193], v[108:109], v[192:193]
	v_pk_add_f32 v[194:195], v[110:111], v[194:195]
	v_pk_add_f32 v[196:197], v[104:105], v[196:197]
	v_pk_add_f32 v[198:199], v[106:107], v[198:199]
	v_cvt_pk_bf16_f32 v248, v192, v193
	v_cvt_pk_bf16_f32 v249, v194, v195
	v_cvt_pk_bf16_f32 v250, v196, v197
	v_cvt_pk_bf16_f32 v251, v198, v199
	global_store_dwordx4 v144, v[248:251], s[66:67]
	v_mul_f32_e32 v193, v193, v193
	v_mul_f32_e32 v195, v195, v195
	v_mul_f32_e32 v197, v197, v197
	v_mul_f32_e32 v199, v199, v199
	v_fmac_f32_e32 v193, v192, v192
	v_fmac_f32_e32 v195, v194, v194
	v_fmac_f32_e32 v197, v196, v196
	v_fmac_f32_e32 v199, v198, v198
	v_add_f32_e32 v145, v193, v195
	v_add_f32_e32 v145, v145, v197
	v_add_f32_e32 v163, v199, v145
	v_pk_add_f32 v[200:201], v[100:101], v[200:201]
	v_pk_add_f32 v[202:203], v[102:103], v[202:203]
	v_pk_add_f32 v[204:205], v[96:97], v[204:205]
	v_pk_add_f32 v[206:207], v[98:99], v[206:207]
	v_cvt_pk_bf16_f32 v248, v200, v201
	v_cvt_pk_bf16_f32 v249, v202, v203
	v_cvt_pk_bf16_f32 v250, v204, v205
	v_cvt_pk_bf16_f32 v251, v206, v207
	global_store_dwordx4 v144, v[248:251], s[66:67] offset:256
	v_mul_f32_e32 v201, v201, v201
	v_mul_f32_e32 v203, v203, v203
	v_mul_f32_e32 v205, v205, v205
	v_mul_f32_e32 v207, v207, v207
	v_fmac_f32_e32 v201, v200, v200
	v_fmac_f32_e32 v203, v202, v202
	v_fmac_f32_e32 v205, v204, v204
	v_fmac_f32_e32 v207, v206, v206
	v_add_f32_e32 v145, v201, v203
	v_add_f32_e32 v145, v145, v205
	v_add_f32_e32 v145, v207, v145
	v_add_f32_e32 v163, v163, v145
	global_load_dwordx4 v[192:195], v245, s[44:45] nt
	global_load_dwordx4 v[196:199], v245, s[44:45] offset:16 nt
	global_load_dwordx4 v[200:203], v245, s[44:45] offset:512 nt
	global_load_dwordx4 v[204:207], v245, s[44:45] offset:528 nt
	s_waitcnt vmcnt(16)
; DI u32x4 pack8f(const f32x4& a, const f32x4& b) { u32x4 w; w.x = pk2(a[0], a[1]); w.y = pk2(a[2], a[3]); w.z = pk2(b[0], b[1]); w.w = pk2(b[2], b[3]); return w; }
;     __device__ __forceinline__ void operator()(const f32x4 (&acc)[2][2][4][2], const Unit& u, int wr, int wc, int fr, int fq) const {
;     ...
;                     const f32x4 v0 = acc[ai][bj][m][0] + __builtin_nontemporal_load((const f32x4*)(xrow + col)), v1 = acc[ai][bj][m][1] + __builtin_nontemporal_load((const f32x4*)(xrow + col + 4));
;                     ss += (v0[0] * v0[0] + v0[1] * v0[1]) + (v0[2] * v0[2] + v0[3] * v0[3]) + (v1[0] * v1[0] + v1[1] * v1[1]) + (v1[2] * v1[2] + v1[3] * v1[3]);
;                     *(u32x4*)(X1B + (size_t)row * DM + col) = pack8f(v0, v1);
;                 }
;                 ss += __shfl_xor(ss, 16); ss += __shfl_xor(ss, 32);
	v_lshrrev_b32_e32 v144, 1, v242
	v_pk_add_f32 v[208:209], v[92:93], v[208:209]
	v_pk_add_f32 v[210:211], v[94:95], v[210:211]
	v_pk_add_f32 v[212:213], v[88:89], v[212:213]
	v_pk_add_f32 v[214:215], v[90:91], v[214:215]
	v_cvt_pk_bf16_f32 v248, v208, v209
	v_cvt_pk_bf16_f32 v249, v210, v211
	v_cvt_pk_bf16_f32 v250, v212, v213
	v_cvt_pk_bf16_f32 v251, v214, v215
	global_store_dwordx4 v144, v[248:251], s[66:67]
	v_mul_f32_e32 v209, v209, v209
	v_mul_f32_e32 v211, v211, v211
	v_mul_f32_e32 v213, v213, v213
	v_mul_f32_e32 v215, v215, v215
	v_fmac_f32_e32 v209, v208, v208
	v_fmac_f32_e32 v211, v210, v210
	v_fmac_f32_e32 v213, v212, v212
	v_fmac_f32_e32 v215, v214, v214
	v_add_f32_e32 v145, v209, v211
	v_add_f32_e32 v145, v145, v213
	v_add_f32_e32 v164, v215, v145
	v_pk_add_f32 v[216:217], v[84:85], v[216:217]
	v_pk_add_f32 v[218:219], v[86:87], v[218:219]
	v_pk_add_f32 v[220:221], v[80:81], v[220:221]
	v_pk_add_f32 v[222:223], v[82:83], v[222:223]
	v_cvt_pk_bf16_f32 v248, v216, v217
	v_cvt_pk_bf16_f32 v249, v218, v219
	v_cvt_pk_bf16_f32 v250, v220, v221
	v_cvt_pk_bf16_f32 v251, v222, v223
	global_store_dwordx4 v144, v[248:251], s[66:67] offset:256
	v_mul_f32_e32 v217, v217, v217
	v_mul_f32_e32 v219, v219, v219
	v_mul_f32_e32 v221, v221, v221
	v_mul_f32_e32 v223, v223, v223
	v_fmac_f32_e32 v217, v216, v216
	v_fmac_f32_e32 v219, v218, v218
	v_fmac_f32_e32 v221, v220, v220
	v_fmac_f32_e32 v223, v222, v222
	v_add_f32_e32 v145, v217, v219
	v_add_f32_e32 v145, v145, v221
	v_add_f32_e32 v145, v223, v145
	v_add_f32_e32 v164, v164, v145
	global_load_dwordx4 v[208:211], v246, s[44:45] nt
	global_load_dwordx4 v[212:215], v246, s[44:45] offset:16 nt
	global_load_dwordx4 v[216:219], v246, s[44:45] offset:512 nt
	global_load_dwordx4 v[220:223], v246, s[44:45] offset:528 nt
	s_waitcnt vmcnt(18)
	v_lshrrev_b32_e32 v144, 1, v243
	v_pk_add_f32 v[224:225], v[76:77], v[224:225]
	v_pk_add_f32 v[226:227], v[78:79], v[226:227]
	v_pk_add_f32 v[228:229], v[72:73], v[228:229]
	v_pk_add_f32 v[230:231], v[74:75], v[230:231]
	v_cvt_pk_bf16_f32 v248, v224, v225
	v_cvt_pk_bf16_f32 v249, v226, v227
	v_cvt_pk_bf16_f32 v250, v228, v229
	v_cvt_pk_bf16_f32 v251, v230, v231
	global_store_dwordx4 v144, v[248:251], s[66:67]
	v_mul_f32_e32 v225, v225, v225
	v_mul_f32_e32 v227, v227, v227
	v_mul_f32_e32 v229, v229, v229
	v_mul_f32_e32 v231, v231, v231
	v_fmac_f32_e32 v225, v224, v224
	v_fmac_f32_e32 v227, v226, v226
	v_fmac_f32_e32 v229, v228, v228
	v_fmac_f32_e32 v231, v230, v230
	v_add_f32_e32 v145, v225, v227
	v_add_f32_e32 v145, v145, v229
	v_add_f32_e32 v165, v231, v145
	v_pk_add_f32 v[232:233], v[68:69], v[232:233]
	v_pk_add_f32 v[234:235], v[70:71], v[234:235]
	v_pk_add_f32 v[236:237], v[64:65], v[236:237]
	v_pk_add_f32 v[238:239], v[66:67], v[238:239]
	v_cvt_pk_bf16_f32 v248, v232, v233
	v_cvt_pk_bf16_f32 v249, v234, v235
	v_cvt_pk_bf16_f32 v250, v236, v237
	v_cvt_pk_bf16_f32 v251, v238, v239
	global_store_dwordx4 v144, v[248:251], s[66:67] offset:256
	v_mul_f32_e32 v233, v233, v233
	v_mul_f32_e32 v235, v235, v235
	v_mul_f32_e32 v237, v237, v237
	v_mul_f32_e32 v239, v239, v239
	v_fmac_f32_e32 v233, v232, v232
	v_fmac_f32_e32 v235, v234, v234
	v_fmac_f32_e32 v237, v236, v236
	v_fmac_f32_e32 v239, v238, v238
	v_add_f32_e32 v145, v233, v235
	v_add_f32_e32 v145, v145, v237
	v_add_f32_e32 v145, v239, v145
	v_add_f32_e32 v165, v165, v145
	global_load_dwordx4 v[224:227], v247, s[44:45] nt
	global_load_dwordx4 v[228:231], v247, s[44:45] offset:16 nt
	global_load_dwordx4 v[232:235], v247, s[44:45] offset:512 nt
	global_load_dwordx4 v[236:239], v247, s[44:45] offset:528 nt
	s_waitcnt vmcnt(18)
	v_lshrrev_b32_e32 v144, 1, v244
	v_pk_add_f32 v[176:177], v[60:61], v[176:177]
	v_pk_add_f32 v[178:179], v[62:63], v[178:179]
	v_pk_add_f32 v[180:181], v[56:57], v[180:181]
	v_pk_add_f32 v[182:183], v[58:59], v[182:183]
	v_cvt_pk_bf16_f32 v248, v176, v177
	v_cvt_pk_bf16_f32 v249, v178, v179
	v_cvt_pk_bf16_f32 v250, v180, v181
	v_cvt_pk_bf16_f32 v251, v182, v183
	global_store_dwordx4 v144, v[248:251], s[66:67]
	v_mul_f32_e32 v177, v177, v177
	v_mul_f32_e32 v179, v179, v179
	v_mul_f32_e32 v181, v181, v181
	v_mul_f32_e32 v183, v183, v183
	v_fmac_f32_e32 v177, v176, v176
	v_fmac_f32_e32 v179, v178, v178
	v_fmac_f32_e32 v181, v180, v180
	v_fmac_f32_e32 v183, v182, v182
	v_add_f32_e32 v145, v177, v179
	v_add_f32_e32 v145, v145, v181
	v_add_f32_e32 v166, v183, v145
	v_pk_add_f32 v[184:185], v[52:53], v[184:185]
	v_pk_add_f32 v[186:187], v[54:55], v[186:187]
	v_pk_add_f32 v[188:189], v[48:49], v[188:189]
	v_pk_add_f32 v[190:191], v[50:51], v[190:191]
	v_cvt_pk_bf16_f32 v248, v184, v185
	v_cvt_pk_bf16_f32 v249, v186, v187
	v_cvt_pk_bf16_f32 v250, v188, v189
	v_cvt_pk_bf16_f32 v251, v190, v191
	global_store_dwordx4 v144, v[248:251], s[66:67] offset:256
	v_mul_f32_e32 v185, v185, v185
	v_mul_f32_e32 v187, v187, v187
	v_mul_f32_e32 v189, v189, v189
	v_mul_f32_e32 v191, v191, v191
	v_fmac_f32_e32 v185, v184, v184
	v_fmac_f32_e32 v187, v186, v186
	v_fmac_f32_e32 v189, v188, v188
	v_fmac_f32_e32 v191, v190, v190
	v_add_f32_e32 v145, v185, v187
	v_add_f32_e32 v145, v145, v189
	v_add_f32_e32 v145, v191, v145
	v_add_f32_e32 v166, v166, v145
	s_waitcnt vmcnt(14)
; DI u32x4 pack8f(const f32x4& a, const f32x4& b) { u32x4 w; w.x = pk2(a[0], a[1]); w.y = pk2(a[2], a[3]); w.z = pk2(b[0], b[1]); w.w = pk2(b[2], b[3]); return w; }
;     __device__ __forceinline__ void operator()(const f32x4 (&acc)[2][2][4][2], const Unit& u, int wr, int wc, int fr, int fq) const {
;     ...
;                     const f32x4 v0 = acc[ai][bj][m][0] + __builtin_nontemporal_load((const f32x4*)(xrow + col)), v1 = acc[ai][bj][m][1] + __builtin_nontemporal_load((const f32x4*)(xrow + col + 4));
;                     ss += (v0[0] * v0[0] + v0[1] * v0[1]) + (v0[2] * v0[2] + v0[3] * v0[3]) + (v1[0] * v1[0] + v1[1] * v1[1]) + (v1[2] * v1[2] + v1[3] * v1[3]);
;                     *(u32x4*)(X1B + (size_t)row * DM + col) = pack8f(v0, v1);
;                 }
;                 ss += __shfl_xor(ss, 16); ss += __shfl_xor(ss, 32);
;                 if (fq == 0) part[(size_t)row * 32 + u.pn * 4 + wc] = ss;
	v_lshrrev_b32_e32 v144, 1, v245
	v_pk_add_f32 v[192:193], v[44:45], v[192:193]
	v_pk_add_f32 v[194:195], v[46:47], v[194:195]
	v_pk_add_f32 v[196:197], v[40:41], v[196:197]
	v_pk_add_f32 v[198:199], v[42:43], v[198:199]
	v_cvt_pk_bf16_f32 v248, v192, v193
	v_cvt_pk_bf16_f32 v249, v194, v195
	v_cvt_pk_bf16_f32 v250, v196, v197
	v_cvt_pk_bf16_f32 v251, v198, v199
	global_store_dwordx4 v144, v[248:251], s[66:67]
	v_mul_f32_e32 v193, v193, v193
	v_mul_f32_e32 v195, v195, v195
	v_mul_f32_e32 v197, v197, v197
	v_mul_f32_e32 v199, v199, v199
	v_fmac_f32_e32 v193, v192, v192
	v_fmac_f32_e32 v195, v194, v194
	v_fmac_f32_e32 v197, v196, v196
	v_fmac_f32_e32 v199, v198, v198
	v_add_f32_e32 v145, v193, v195
	v_add_f32_e32 v145, v145, v197
	v_add_f32_e32 v167, v199, v145
	v_pk_add_f32 v[200:201], v[36:37], v[200:201]
	v_pk_add_f32 v[202:203], v[38:39], v[202:203]
	v_pk_add_f32 v[204:205], v[32:33], v[204:205]
	v_pk_add_f32 v[206:207], v[34:35], v[206:207]
	v_cvt_pk_bf16_f32 v248, v200, v201
	v_cvt_pk_bf16_f32 v249, v202, v203
	v_cvt_pk_bf16_f32 v250, v204, v205
	v_cvt_pk_bf16_f32 v251, v206, v207
	global_store_dwordx4 v144, v[248:251], s[66:67] offset:256
	v_mul_f32_e32 v201, v201, v201
	v_mul_f32_e32 v203, v203, v203
	v_mul_f32_e32 v205, v205, v205
	v_mul_f32_e32 v207, v207, v207
	v_fmac_f32_e32 v201, v200, v200
	v_fmac_f32_e32 v203, v202, v202
	v_fmac_f32_e32 v205, v204, v204
	v_fmac_f32_e32 v207, v206, v206
	v_add_f32_e32 v145, v201, v203
	v_add_f32_e32 v145, v145, v205
	v_add_f32_e32 v145, v207, v145
	v_add_f32_e32 v167, v167, v145
	s_waitcnt vmcnt(10)
	v_lshrrev_b32_e32 v144, 1, v246
	v_pk_add_f32 v[208:209], v[28:29], v[208:209]
	v_pk_add_f32 v[210:211], v[30:31], v[210:211]
	v_pk_add_f32 v[212:213], v[24:25], v[212:213]
	v_pk_add_f32 v[214:215], v[26:27], v[214:215]
	v_cvt_pk_bf16_f32 v248, v208, v209
	v_cvt_pk_bf16_f32 v249, v210, v211
	v_cvt_pk_bf16_f32 v250, v212, v213
	v_cvt_pk_bf16_f32 v251, v214, v215
	global_store_dwordx4 v144, v[248:251], s[66:67]
	v_mul_f32_e32 v209, v209, v209
	v_mul_f32_e32 v211, v211, v211
	v_mul_f32_e32 v213, v213, v213
	v_mul_f32_e32 v215, v215, v215
	v_fmac_f32_e32 v209, v208, v208
	v_fmac_f32_e32 v211, v210, v210
	v_fmac_f32_e32 v213, v212, v212
	v_fmac_f32_e32 v215, v214, v214
	v_add_f32_e32 v145, v209, v211
	v_add_f32_e32 v145, v145, v213
	v_add_f32_e32 v168, v215, v145
	v_pk_add_f32 v[216:217], v[20:21], v[216:217]
	v_pk_add_f32 v[218:219], v[22:23], v[218:219]
	v_pk_add_f32 v[220:221], v[16:17], v[220:221]
	v_pk_add_f32 v[222:223], v[18:19], v[222:223]
	v_cvt_pk_bf16_f32 v248, v216, v217
	v_cvt_pk_bf16_f32 v249, v218, v219
	v_cvt_pk_bf16_f32 v250, v220, v221
	v_cvt_pk_bf16_f32 v251, v222, v223
	global_store_dwordx4 v144, v[248:251], s[66:67] offset:256
	v_mul_f32_e32 v217, v217, v217
	v_mul_f32_e32 v219, v219, v219
	v_mul_f32_e32 v221, v221, v221
	v_mul_f32_e32 v223, v223, v223
	v_fmac_f32_e32 v217, v216, v216
	v_fmac_f32_e32 v219, v218, v218
	v_fmac_f32_e32 v221, v220, v220
	v_fmac_f32_e32 v223, v222, v222
	v_add_f32_e32 v145, v217, v219
	v_add_f32_e32 v145, v145, v221
	v_add_f32_e32 v145, v223, v145
	v_add_f32_e32 v168, v168, v145
	s_waitcnt vmcnt(6)
	v_lshrrev_b32_e32 v144, 1, v247
	v_pk_add_f32 v[224:225], v[12:13], v[224:225]
	v_pk_add_f32 v[226:227], v[14:15], v[226:227]
	v_pk_add_f32 v[228:229], v[8:9], v[228:229]
	v_pk_add_f32 v[230:231], v[10:11], v[230:231]
	v_cvt_pk_bf16_f32 v248, v224, v225
	v_cvt_pk_bf16_f32 v249, v226, v227
	v_cvt_pk_bf16_f32 v250, v228, v229
	v_cvt_pk_bf16_f32 v251, v230, v231
	global_store_dwordx4 v144, v[248:251], s[66:67]
	v_mul_f32_e32 v225, v225, v225
	v_mul_f32_e32 v227, v227, v227
	v_mul_f32_e32 v229, v229, v229
	v_mul_f32_e32 v231, v231, v231
	v_fmac_f32_e32 v225, v224, v224
	v_fmac_f32_e32 v227, v226, v226
	v_fmac_f32_e32 v229, v228, v228
	v_fmac_f32_e32 v231, v230, v230
	v_add_f32_e32 v145, v225, v227
	v_add_f32_e32 v145, v145, v229
	v_add_f32_e32 v169, v231, v145
	v_pk_add_f32 v[232:233], v[4:5], v[232:233]
	v_pk_add_f32 v[234:235], v[6:7], v[234:235]
	v_pk_add_f32 v[236:237], v[0:1], v[236:237]
	v_pk_add_f32 v[238:239], v[2:3], v[238:239]
	v_cvt_pk_bf16_f32 v248, v232, v233
	v_cvt_pk_bf16_f32 v249, v234, v235
	v_cvt_pk_bf16_f32 v250, v236, v237
	v_cvt_pk_bf16_f32 v251, v238, v239
	global_store_dwordx4 v144, v[248:251], s[66:67] offset:256
	v_mul_f32_e32 v233, v233, v233
	v_mul_f32_e32 v235, v235, v235
	v_mul_f32_e32 v237, v237, v237
	v_mul_f32_e32 v239, v239, v239
	v_fmac_f32_e32 v233, v232, v232
	v_fmac_f32_e32 v235, v234, v234
	v_fmac_f32_e32 v237, v236, v236
	v_fmac_f32_e32 v239, v238, v238
	v_add_f32_e32 v145, v233, v235
	v_add_f32_e32 v145, v145, v237
	v_add_f32_e32 v145, v239, v145
	v_add_f32_e32 v169, v169, v145
	ds_bpermute_b32 v176, v172, v162
	ds_bpermute_b32 v177, v172, v163
	ds_bpermute_b32 v178, v172, v164
	ds_bpermute_b32 v179, v172, v165
	ds_bpermute_b32 v180, v172, v166
	ds_bpermute_b32 v181, v172, v167
	ds_bpermute_b32 v182, v172, v168
	ds_bpermute_b32 v183, v172, v169
	s_waitcnt lgkmcnt(7)
	v_add_f32_e32 v162, v162, v176
	s_waitcnt lgkmcnt(6)
	v_add_f32_e32 v163, v163, v177
	s_waitcnt lgkmcnt(5)
	v_add_f32_e32 v164, v164, v178
	s_waitcnt lgkmcnt(4)
	v_add_f32_e32 v165, v165, v179
	s_waitcnt lgkmcnt(3)
	v_add_f32_e32 v166, v166, v180
	s_waitcnt lgkmcnt(2)
	v_add_f32_e32 v167, v167, v181
	s_waitcnt lgkmcnt(1)
	v_add_f32_e32 v168, v168, v182
	s_waitcnt lgkmcnt(0)
	v_add_f32_e32 v169, v169, v183
	ds_bpermute_b32 v176, v173, v162
	ds_bpermute_b32 v177, v173, v163
	ds_bpermute_b32 v178, v173, v164
	ds_bpermute_b32 v179, v173, v165
	ds_bpermute_b32 v180, v173, v166
	ds_bpermute_b32 v181, v173, v167
	ds_bpermute_b32 v182, v173, v168
	ds_bpermute_b32 v183, v173, v169
	s_lshl_b32 s26, s8, 4
	s_lshl_b32 s27, s40, 2
	s_add_i32 s26, s26, s27
	v_lshl_add_u32 v146, v170, 7, s26
	s_waitcnt lgkmcnt(7)
	v_add_f32_e32 v162, v162, v176
	s_waitcnt lgkmcnt(6)
	v_add_f32_e32 v163, v163, v177
	s_waitcnt lgkmcnt(5)
	v_add_f32_e32 v164, v164, v178
	s_waitcnt lgkmcnt(4)
	v_add_f32_e32 v165, v165, v179
	s_waitcnt lgkmcnt(3)
	v_add_f32_e32 v166, v166, v180
	s_waitcnt lgkmcnt(2)
	v_add_f32_e32 v167, v167, v181
	s_waitcnt lgkmcnt(1)
	v_add_f32_e32 v168, v168, v182
	s_waitcnt lgkmcnt(0)
	v_add_f32_e32 v169, v169, v183
	s_and_saveexec_b64 s[2:3], s[0:1]
	global_store_dword v146, v162, s[12:13]
	v_add_u32_e32 v174, 0x800, v146
	global_store_dword v174, v163, s[12:13]
	v_add_u32_e32 v174, 0x1000, v146
	global_store_dword v174, v164, s[12:13]
	v_add_u32_e32 v174, 0x1800, v146
	global_store_dword v174, v165, s[12:13]
	v_add_u32_e32 v174, 0x4000, v146
	global_store_dword v174, v166, s[12:13]
	v_add_u32_e32 v174, 0x4800, v146
	global_store_dword v174, v167, s[12:13]
	v_add_u32_e32 v174, 0x5000, v146
	global_store_dword v174, v168, s[12:13]
	v_add_u32_e32 v174, 0x5800, v146
	global_store_dword v174, v169, s[12:13]
	s_or_b64 exec, exec, s[2:3]
	s_mov_b64 s[2:3], exec

; DI float bflo(unsigned u) { return __uint_as_float(u << 16); }
; DI float bfhi(unsigned u) { return __uint_as_float(u & 0xffff0000u); }
;     __device__ __forceinline__ void operator()(const f32x4 (&acc)[2][2][4][2], const Unit& u, int wr, int wc, int fr, int fq) const {
;     ...
;                 const int row = u.pm * BM + ai * HALF + wr * 64 + m * 16 + fr; const float r2 = rstd2[row];
; #pragma unroll
;                 for (int bj = 0; bj < 2; ++bj) { const size_t o = (size_t)row * DM + u.pn * BM + bj * HALF + wc * 32 + 8 * fq;
;                     const u32x4 xb = *(const u32x4*)(X1B + o);
;                     const f32x4 a = {bflo(xb.x), bfhi(xb.x), bflo(xb.y), bfhi(xb.y)}, b = {bflo(xb.z), bfhi(xb.z), bflo(xb.w), bfhi(xb.w)};
;                     *(f32x4*)(Y + o) = a + acc[ai][bj][m][0] * r2; *(f32x4*)(Y + o + 4) = b + acc[ai][bj][m][1] * r2; }
.LBB0_720:
	v_lshl_add_u32 v170, s26, 8, v131
	s_lshl_b32 s2, s45, 8
	v_readlane_b32 s30, v254, 21
	v_readlane_b32 s31, v254, 22
	v_or_b32_e32 v171, s2, v140
	v_lshl_add_u32 v172, v170, 11, v171
	v_lshlrev_b32_e32 v165, 2, v170
	v_lshlrev_b32_e32 v241, 1, v172
	v_add_u32_e32 v243, 0x10000, v241
	v_add_u32_e32 v245, 0x20000, v241
	v_add_u32_e32 v247, 0x30000, v241
	v_add_u32_e32 v249, 0x80000, v241
	v_add_u32_e32 v251, 0x90000, v241
	v_add_u32_e32 v161, 0xa0000, v241
	v_add_u32_e32 v163, 0xb0000, v241
	global_load_dword v240, v165, s[4:5] offset:0
	global_load_dwordx4 v[176:179], v241, s[66:67]
	global_load_dwordx4 v[180:183], v241, s[66:67] offset:256
	global_load_dword v242, v165, s[4:5] offset:64
	global_load_dwordx4 v[184:187], v243, s[66:67]
	global_load_dwordx4 v[188:191], v243, s[66:67] offset:256
	global_load_dword v244, v165, s[4:5] offset:128
	global_load_dwordx4 v[192:195], v245, s[66:67]
	global_load_dwordx4 v[196:199], v245, s[66:67] offset:256
	global_load_dword v246, v165, s[4:5] offset:192
	global_load_dwordx4 v[200:203], v247, s[66:67]
	global_load_dwordx4 v[204:207], v247, s[66:67] offset:256
	global_load_dword v248, v165, s[4:5] offset:512
	global_load_dwordx4 v[208:211], v249, s[66:67]
	global_load_dwordx4 v[212:215], v249, s[66:67] offset:256
	global_load_dword v250, v165, s[4:5] offset:576
	global_load_dwordx4 v[216:219], v251, s[66:67]
	global_load_dwordx4 v[220:223], v251, s[66:67] offset:256
	global_load_dword v162, v165, s[4:5] offset:640
	global_load_dwordx4 v[224:227], v161, s[66:67]
	global_load_dwordx4 v[228:231], v161, s[66:67] offset:256
	global_load_dword v164, v165, s[4:5] offset:704
	global_load_dwordx4 v[232:235], v163, s[66:67]
	global_load_dwordx4 v[236:239], v163, s[66:67] offset:256
	s_andn2_b64 vcc, exec, s[0:1]
	s_mov_b64 s[0:1], -1
	s_waitcnt vmcnt(22)
	v_lshlrev_b32_e32 v173, 1, v241
	v_lshlrev_b32_e32 v150, 16, v176
	v_and_b32_e32 v151, 0xffff0000, v176
	v_lshlrev_b32_e32 v152, 16, v177
	v_and_b32_e32 v153, 0xffff0000, v177
	v_lshlrev_b32_e32 v166, 16, v178
	v_and_b32_e32 v167, 0xffff0000, v178
	v_lshlrev_b32_e32 v168, 16, v179
	v_and_b32_e32 v169, 0xffff0000, v179
	v_pk_fma_f32 v[124:125], v[124:125], v[240:241], v[150:151] op_sel_hi:[1,0,1]
	v_pk_fma_f32 v[126:127], v[126:127], v[240:241], v[152:153] op_sel_hi:[1,0,1]
	v_pk_fma_f32 v[120:121], v[120:121], v[240:241], v[166:167] op_sel_hi:[1,0,1]
	v_pk_fma_f32 v[122:123], v[122:123], v[240:241], v[168:169] op_sel_hi:[1,0,1]
	global_store_dwordx4 v173, v[124:127], s[30:31]
	global_store_dwordx4 v173, v[120:123], s[30:31] offset:16
	s_waitcnt vmcnt(23)
	v_lshlrev_b32_e32 v150, 16, v180
	v_and_b32_e32 v151, 0xffff0000, v180
	v_lshlrev_b32_e32 v152, 16, v181
	v_and_b32_e32 v153, 0xffff0000, v181
	v_lshlrev_b32_e32 v166, 16, v182
	v_and_b32_e32 v167, 0xffff0000, v182
	v_lshlrev_b32_e32 v168, 16, v183
	v_and_b32_e32 v169, 0xffff0000, v183
	v_pk_fma_f32 v[116:117], v[116:117], v[240:241], v[150:151] op_sel_hi:[1,0,1]
	v_pk_fma_f32 v[118:119], v[118:119], v[240:241], v[152:153] op_sel_hi:[1,0,1]
	v_pk_fma_f32 v[112:113], v[112:113], v[240:241], v[166:167] op_sel_hi:[1,0,1]
	v_pk_fma_f32 v[114:115], v[114:115], v[240:241], v[168:169] op_sel_hi:[1,0,1]
	global_store_dwordx4 v173, v[116:119], s[30:31] offset:512
	global_store_dwordx4 v173, v[112:115], s[30:31] offset:528
	s_waitcnt vmcnt(23)
	v_lshlrev_b32_e32 v173, 1, v243
	v_lshlrev_b32_e32 v150, 16, v184
	v_and_b32_e32 v151, 0xffff0000, v184
	v_lshlrev_b32_e32 v152, 16, v185
	v_and_b32_e32 v153, 0xffff0000, v185
	v_lshlrev_b32_e32 v166, 16, v186
	v_and_b32_e32 v167, 0xffff0000, v186
	v_lshlrev_b32_e32 v168, 16, v187
	v_and_b32_e32 v169, 0xffff0000, v187
	v_pk_fma_f32 v[108:109], v[108:109], v[242:243], v[150:151] op_sel_hi:[1,0,1]
	v_pk_fma_f32 v[110:111], v[110:111], v[242:243], v[152:153] op_sel_hi:[1,0,1]
	v_pk_fma_f32 v[104:105], v[104:105], v[242:243], v[166:167] op_sel_hi:[1,0,1]
	v_pk_fma_f32 v[106:107], v[106:107], v[242:243], v[168:169] op_sel_hi:[1,0,1]
	global_store_dwordx4 v173, v[108:111], s[30:31]
	global_store_dwordx4 v173, v[104:107], s[30:31] offset:16
	s_waitcnt vmcnt(24)
	v_lshlrev_b32_e32 v150, 16, v188
	v_and_b32_e32 v151, 0xffff0000, v188
	v_lshlrev_b32_e32 v152, 16, v189
	v_and_b32_e32 v153, 0xffff0000, v189
	v_lshlrev_b32_e32 v166, 16, v190
	v_and_b32_e32 v167, 0xffff0000, v190
	v_lshlrev_b32_e32 v168, 16, v191
	v_and_b32_e32 v169, 0xffff0000, v191
	v_pk_fma_f32 v[100:101], v[100:101], v[242:243], v[150:151] op_sel_hi:[1,0,1]
	v_pk_fma_f32 v[102:103], v[102:103], v[242:243], v[152:153] op_sel_hi:[1,0,1]
	v_pk_fma_f32 v[96:97], v[96:97], v[242:243], v[166:167] op_sel_hi:[1,0,1]
	v_pk_fma_f32 v[98:99], v[98:99], v[242:243], v[168:169] op_sel_hi:[1,0,1]
	global_store_dwordx4 v173, v[100:103], s[30:31] offset:512
	global_store_dwordx4 v173, v[96:99], s[30:31] offset:528
	s_waitcnt vmcnt(24)
	v_lshlrev_b32_e32 v173, 1, v245
	v_lshlrev_b32_e32 v150, 16, v192
	v_and_b32_e32 v151, 0xffff0000, v192
	v_lshlrev_b32_e32 v152, 16, v193
	v_and_b32_e32 v153, 0xffff0000, v193
	v_lshlrev_b32_e32 v166, 16, v194
	v_and_b32_e32 v167, 0xffff0000, v194
	v_lshlrev_b32_e32 v168, 16, v195
	v_and_b32_e32 v169, 0xffff0000, v195
	v_pk_fma_f32 v[92:93], v[92:93], v[244:245], v[150:151] op_sel_hi:[1,0,1]
	v_pk_fma_f32 v[94:95], v[94:95], v[244:245], v[152:153] op_sel_hi:[1,0,1]
	v_pk_fma_f32 v[88:89], v[88:89], v[244:245], v[166:167] op_sel_hi:[1,0,1]
	v_pk_fma_f32 v[90:91], v[90:91], v[244:245], v[168:169] op_sel_hi:[1,0,1]
	global_store_dwordx4 v173, v[92:95], s[30:31]
	global_store_dwordx4 v173, v[88:91], s[30:31] offset:16
	s_waitcnt vmcnt(25)
; DI float bflo(unsigned u) { return __uint_as_float(u << 16); }
; DI float bfhi(unsigned u) { return __uint_as_float(u & 0xffff0000u); }
;     __device__ __forceinline__ void operator()(const f32x4 (&acc)[2][2][4][2], const Unit& u, int wr, int wc, int fr, int fq) const {
;     ...
;                 for (int bj = 0; bj < 2; ++bj) { const size_t o = (size_t)row * DM + u.pn * BM + bj * HALF + wc * 32 + 8 * fq;
;                     const u32x4 xb = *(const u32x4*)(X1B + o);
;                     const f32x4 a = {bflo(xb.x), bfhi(xb.x), bflo(xb.y), bfhi(xb.y)}, b = {bflo(xb.z), bfhi(xb.z), bflo(xb.w), bfhi(xb.w)};
;                     *(f32x4*)(Y + o) = a + acc[ai][bj][m][0] * r2; *(f32x4*)(Y + o + 4) = b + acc[ai][bj][m][1] * r2; }
	v_lshlrev_b32_e32 v150, 16, v196
	v_and_b32_e32 v151, 0xffff0000, v196
	v_lshlrev_b32_e32 v152, 16, v197
	v_and_b32_e32 v153, 0xffff0000, v197
	v_lshlrev_b32_e32 v166, 16, v198
	v_and_b32_e32 v167, 0xffff0000, v198
	v_lshlrev_b32_e32 v168, 16, v199
	v_and_b32_e32 v169, 0xffff0000, v199
	v_pk_fma_f32 v[84:85], v[84:85], v[244:245], v[150:151] op_sel_hi:[1,0,1]
	v_pk_fma_f32 v[86:87], v[86:87], v[244:245], v[152:153] op_sel_hi:[1,0,1]
	v_pk_fma_f32 v[80:81], v[80:81], v[244:245], v[166:167] op_sel_hi:[1,0,1]
	v_pk_fma_f32 v[82:83], v[82:83], v[244:245], v[168:169] op_sel_hi:[1,0,1]
	global_store_dwordx4 v173, v[84:87], s[30:31] offset:512
	global_store_dwordx4 v173, v[80:83], s[30:31] offset:528
	s_waitcnt vmcnt(25)
	v_lshlrev_b32_e32 v173, 1, v247
	v_lshlrev_b32_e32 v150, 16, v200
	v_and_b32_e32 v151, 0xffff0000, v200
	v_lshlrev_b32_e32 v152, 16, v201
	v_and_b32_e32 v153, 0xffff0000, v201
	v_lshlrev_b32_e32 v166, 16, v202
	v_and_b32_e32 v167, 0xffff0000, v202
	v_lshlrev_b32_e32 v168, 16, v203
	v_and_b32_e32 v169, 0xffff0000, v203
	v_pk_fma_f32 v[76:77], v[76:77], v[246:247], v[150:151] op_sel_hi:[1,0,1]
	v_pk_fma_f32 v[78:79], v[78:79], v[246:247], v[152:153] op_sel_hi:[1,0,1]
	v_pk_fma_f32 v[72:73], v[72:73], v[246:247], v[166:167] op_sel_hi:[1,0,1]
	v_pk_fma_f32 v[74:75], v[74:75], v[246:247], v[168:169] op_sel_hi:[1,0,1]
	global_store_dwordx4 v173, v[76:79], s[30:31]
	global_store_dwordx4 v173, v[72:75], s[30:31] offset:16
	s_waitcnt vmcnt(26)
	v_lshlrev_b32_e32 v150, 16, v204
	v_and_b32_e32 v151, 0xffff0000, v204
	v_lshlrev_b32_e32 v152, 16, v205
	v_and_b32_e32 v153, 0xffff0000, v205
	v_lshlrev_b32_e32 v166, 16, v206
	v_and_b32_e32 v167, 0xffff0000, v206
	v_lshlrev_b32_e32 v168, 16, v207
	v_and_b32_e32 v169, 0xffff0000, v207
	v_pk_fma_f32 v[68:69], v[68:69], v[246:247], v[150:151] op_sel_hi:[1,0,1]
	v_pk_fma_f32 v[70:71], v[70:71], v[246:247], v[152:153] op_sel_hi:[1,0,1]
	v_pk_fma_f32 v[64:65], v[64:65], v[246:247], v[166:167] op_sel_hi:[1,0,1]
	v_pk_fma_f32 v[66:67], v[66:67], v[246:247], v[168:169] op_sel_hi:[1,0,1]
	global_store_dwordx4 v173, v[68:71], s[30:31] offset:512
	global_store_dwordx4 v173, v[64:67], s[30:31] offset:528
	s_waitcnt vmcnt(26)
	v_lshlrev_b32_e32 v173, 1, v249
	v_lshlrev_b32_e32 v150, 16, v208
	v_and_b32_e32 v151, 0xffff0000, v208
	v_lshlrev_b32_e32 v152, 16, v209
	v_and_b32_e32 v153, 0xffff0000, v209
	v_lshlrev_b32_e32 v166, 16, v210
	v_and_b32_e32 v167, 0xffff0000, v210
	v_lshlrev_b32_e32 v168, 16, v211
	v_and_b32_e32 v169, 0xffff0000, v211
	v_pk_fma_f32 v[60:61], v[60:61], v[248:249], v[150:151] op_sel_hi:[1,0,1]
	v_pk_fma_f32 v[62:63], v[62:63], v[248:249], v[152:153] op_sel_hi:[1,0,1]
	v_pk_fma_f32 v[56:57], v[56:57], v[248:249], v[166:167] op_sel_hi:[1,0,1]
	v_pk_fma_f32 v[58:59], v[58:59], v[248:249], v[168:169] op_sel_hi:[1,0,1]
	global_store_dwordx4 v173, v[60:63], s[30:31]
	global_store_dwordx4 v173, v[56:59], s[30:31] offset:16
	s_waitcnt vmcnt(27)
	v_lshlrev_b32_e32 v150, 16, v212
	v_and_b32_e32 v151, 0xffff0000, v212
	v_lshlrev_b32_e32 v152, 16, v213
	v_and_b32_e32 v153, 0xffff0000, v213
	v_lshlrev_b32_e32 v166, 16, v214
	v_and_b32_e32 v167, 0xffff0000, v214
	v_lshlrev_b32_e32 v168, 16, v215
	v_and_b32_e32 v169, 0xffff0000, v215
	v_pk_fma_f32 v[52:53], v[52:53], v[248:249], v[150:151] op_sel_hi:[1,0,1]
	v_pk_fma_f32 v[54:55], v[54:55], v[248:249], v[152:153] op_sel_hi:[1,0,1]
	v_pk_fma_f32 v[48:49], v[48:49], v[248:249], v[166:167] op_sel_hi:[1,0,1]
	v_pk_fma_f32 v[50:51], v[50:51], v[248:249], v[168:169] op_sel_hi:[1,0,1]
	global_store_dwordx4 v173, v[52:55], s[30:31] offset:512
	global_store_dwordx4 v173, v[48:51], s[30:31] offset:528
	s_waitcnt vmcnt(27)
	v_lshlrev_b32_e32 v173, 1, v251
	v_lshlrev_b32_e32 v150, 16, v216
	v_and_b32_e32 v151, 0xffff0000, v216
	v_lshlrev_b32_e32 v152, 16, v217
	v_and_b32_e32 v153, 0xffff0000, v217
	v_lshlrev_b32_e32 v166, 16, v218
	v_and_b32_e32 v167, 0xffff0000, v218
	v_lshlrev_b32_e32 v168, 16, v219
	v_and_b32_e32 v169, 0xffff0000, v219
	v_pk_fma_f32 v[44:45], v[44:45], v[250:251], v[150:151] op_sel_hi:[1,0,1]
	v_pk_fma_f32 v[46:47], v[46:47], v[250:251], v[152:153] op_sel_hi:[1,0,1]
	v_pk_fma_f32 v[40:41], v[40:41], v[250:251], v[166:167] op_sel_hi:[1,0,1]
	v_pk_fma_f32 v[42:43], v[42:43], v[250:251], v[168:169] op_sel_hi:[1,0,1]
	global_store_dwordx4 v173, v[44:47], s[30:31]
	global_store_dwordx4 v173, v[40:43], s[30:31] offset:16
	s_waitcnt vmcnt(28)
; DI float bflo(unsigned u) { return __uint_as_float(u << 16); }
; DI float bfhi(unsigned u) { return __uint_as_float(u & 0xffff0000u); }
;     __device__ __forceinline__ void operator()(const f32x4 (&acc)[2][2][4][2], const Unit& u, int wr, int wc, int fr, int fq) const {
;     ...
;                 for (int bj = 0; bj < 2; ++bj) { const size_t o = (size_t)row * DM + u.pn * BM + bj * HALF + wc * 32 + 8 * fq;
;                     const u32x4 xb = *(const u32x4*)(X1B + o);
;                     const f32x4 a = {bflo(xb.x), bfhi(xb.x), bflo(xb.y), bfhi(xb.y)}, b = {bflo(xb.z), bfhi(xb.z), bflo(xb.w), bfhi(xb.w)};
;                     *(f32x4*)(Y + o) = a + acc[ai][bj][m][0] * r2; *(f32x4*)(Y + o + 4) = b + acc[ai][bj][m][1] * r2; }
	v_lshlrev_b32_e32 v150, 16, v220
	v_and_b32_e32 v151, 0xffff0000, v220
	v_lshlrev_b32_e32 v152, 16, v221
	v_and_b32_e32 v153, 0xffff0000, v221
	v_lshlrev_b32_e32 v166, 16, v222
	v_and_b32_e32 v167, 0xffff0000, v222
	v_lshlrev_b32_e32 v168, 16, v223
	v_and_b32_e32 v169, 0xffff0000, v223
	v_pk_fma_f32 v[36:37], v[36:37], v[250:251], v[150:151] op_sel_hi:[1,0,1]
	v_pk_fma_f32 v[38:39], v[38:39], v[250:251], v[152:153] op_sel_hi:[1,0,1]
	v_pk_fma_f32 v[32:33], v[32:33], v[250:251], v[166:167] op_sel_hi:[1,0,1]
	v_pk_fma_f32 v[34:35], v[34:35], v[250:251], v[168:169] op_sel_hi:[1,0,1]
	global_store_dwordx4 v173, v[36:39], s[30:31] offset:512
	global_store_dwordx4 v173, v[32:35], s[30:31] offset:528
	s_waitcnt vmcnt(28)
	v_lshlrev_b32_e32 v173, 1, v161
	v_lshlrev_b32_e32 v150, 16, v224
	v_and_b32_e32 v151, 0xffff0000, v224
	v_lshlrev_b32_e32 v152, 16, v225
	v_and_b32_e32 v153, 0xffff0000, v225
	v_lshlrev_b32_e32 v166, 16, v226
	v_and_b32_e32 v167, 0xffff0000, v226
	v_lshlrev_b32_e32 v168, 16, v227
	v_and_b32_e32 v169, 0xffff0000, v227
	v_pk_fma_f32 v[28:29], v[28:29], v[162:163], v[150:151] op_sel_hi:[1,0,1]
	v_pk_fma_f32 v[30:31], v[30:31], v[162:163], v[152:153] op_sel_hi:[1,0,1]
	v_pk_fma_f32 v[24:25], v[24:25], v[162:163], v[166:167] op_sel_hi:[1,0,1]
	v_pk_fma_f32 v[26:27], v[26:27], v[162:163], v[168:169] op_sel_hi:[1,0,1]
	global_store_dwordx4 v173, v[28:31], s[30:31]
	global_store_dwordx4 v173, v[24:27], s[30:31] offset:16
	s_waitcnt vmcnt(29)
	v_lshlrev_b32_e32 v150, 16, v228
	v_and_b32_e32 v151, 0xffff0000, v228
	v_lshlrev_b32_e32 v152, 16, v229
	v_and_b32_e32 v153, 0xffff0000, v229
	v_lshlrev_b32_e32 v166, 16, v230
	v_and_b32_e32 v167, 0xffff0000, v230
	v_lshlrev_b32_e32 v168, 16, v231
	v_and_b32_e32 v169, 0xffff0000, v231
	v_pk_fma_f32 v[20:21], v[20:21], v[162:163], v[150:151] op_sel_hi:[1,0,1]
	v_pk_fma_f32 v[22:23], v[22:23], v[162:163], v[152:153] op_sel_hi:[1,0,1]
	v_pk_fma_f32 v[16:17], v[16:17], v[162:163], v[166:167] op_sel_hi:[1,0,1]
	v_pk_fma_f32 v[18:19], v[18:19], v[162:163], v[168:169] op_sel_hi:[1,0,1]
	global_store_dwordx4 v173, v[20:23], s[30:31] offset:512
	global_store_dwordx4 v173, v[16:19], s[30:31] offset:528
	s_waitcnt vmcnt(29)
	v_lshlrev_b32_e32 v173, 1, v163
	v_lshlrev_b32_e32 v150, 16, v232
	v_and_b32_e32 v151, 0xffff0000, v232
	v_lshlrev_b32_e32 v152, 16, v233
	v_and_b32_e32 v153, 0xffff0000, v233
	v_lshlrev_b32_e32 v166, 16, v234
	v_and_b32_e32 v167, 0xffff0000, v234
	v_lshlrev_b32_e32 v168, 16, v235
	v_and_b32_e32 v169, 0xffff0000, v235
	v_pk_fma_f32 v[12:13], v[12:13], v[164:165], v[150:151] op_sel_hi:[1,0,1]
	v_pk_fma_f32 v[14:15], v[14:15], v[164:165], v[152:153] op_sel_hi:[1,0,1]
	v_pk_fma_f32 v[8:9], v[8:9], v[164:165], v[166:167] op_sel_hi:[1,0,1]
	v_pk_fma_f32 v[10:11], v[10:11], v[164:165], v[168:169] op_sel_hi:[1,0,1]
	global_store_dwordx4 v173, v[12:15], s[30:31]
	global_store_dwordx4 v173, v[8:11], s[30:31] offset:16
	s_waitcnt vmcnt(30)
	v_lshlrev_b32_e32 v150, 16, v236
	v_and_b32_e32 v151, 0xffff0000, v236
	v_lshlrev_b32_e32 v152, 16, v237
	v_and_b32_e32 v153, 0xffff0000, v237
	v_lshlrev_b32_e32 v166, 16, v238
	v_and_b32_e32 v167, 0xffff0000, v238
	v_lshlrev_b32_e32 v168, 16, v239
	v_and_b32_e32 v169, 0xffff0000, v239
	v_pk_fma_f32 v[4:5], v[4:5], v[164:165], v[150:151] op_sel_hi:[1,0,1]
	v_pk_fma_f32 v[6:7], v[6:7], v[164:165], v[152:153] op_sel_hi:[1,0,1]
	v_pk_fma_f32 v[0:1], v[0:1], v[164:165], v[166:167] op_sel_hi:[1,0,1]
	v_pk_fma_f32 v[2:3], v[2:3], v[164:165], v[168:169] op_sel_hi:[1,0,1]
	global_store_dwordx4 v173, v[4:7], s[30:31] offset:512
	global_store_dwordx4 v173, v[0:3], s[30:31] offset:528
	s_cbranch_vccnz .LBB0_709
	s_andn2_b64 vcc, exec, s[12:13]
	s_cbranch_vccnz .LBB0_708
	s_barrier
	s_branch .LBB0_708
